# attn head loop: next head's Q/sink prefetched one iteration ahead, counted vmcnt(4) keeps O stores in flight
# speedup vs baseline: 1.0055x; 1.0017x over previous
; template <bool LDSRC>
; __device__ __forceinline__ void attn_core(const Params& p, const int lane, const char* kptr, const int kstride, const char* vptr, const int vstride,
;                                           const int kt0, const int has_prev, const int row_q, const int h_q, const int i_q) {
;     ...
;   const int pl = lane & 15, q4 = lane >> 4;
;   const bf16_t* P = (const bf16_t*)(ws + OFF_P);
;   const float sink = p.in[17][h_q];
;   const bf16_t* qp = P + (size_t)row_q * PW + 512 + h_q * 64 + q4 * 8;
;   const bf16x8 qf0 = *(const bf16x8*)qp, qf1 = *(const bf16x8*)(qp + 32);
;   u32x4 vfr[LDSRC ? 1 : 5][4];
;   if constexpr (!LDSRC) {
; #pragma unroll
;     for (int pp = 0; pp < 5; ++pp) {
;       int TA = kt0 + 2 * pp, TB = kt0 + ((2 * pp + 1 < 9) ? 2 * pp + 1 : 2 * pp);
;       if (!has_prev) { if (TA < 8) TA = 8; if (TB < 8) TB = 8; }
; #pragma unroll
;       for (int dt = 0; dt < 4; ++dt) {
;         const char* vp = vptr + (dt * 16 + pl) * vstride + q4 * 8;
;         const u32x2 va = *(const u32x2*)(vp + TA * 32), vb = *(const u32x2*)(vp + TB * 32);
;         vfr[pp][dt] = u32x4{va.x, va.y, vb.x, vb.y};
;       }
;     }
;   }
;   f32x4 sa[9];
; #pragma unroll
;   for (int kt = 0; kt < 9; ++kt) {
;     int T = kt0 + kt; if (!has_prev && T < 8) T = 8;
;     const char* kp = kptr + (T * 16 + pl) * kstride + q4 * 16;
;     bf16x8 k0, k1;
;     if constexpr (LDSRC) { k0 = *(const LAS bf16x8*)(const LAS char*)kp; k1 = *(const LAS bf16x8*)(const LAS char*)(kp + 64); }
;     else { k0 = *(const bf16x8*)kp; k1 = *(const bf16x8*)(kp + 64); }
;     f32x4 a = f32x4{0.f, 0.f, 0.f, 0.f};
;     a = __builtin_amdgcn_mfma_f32_16x16x32_bf16(k0, qf0, a, 0, 0, 0);
;     a = __builtin_amdgcn_mfma_f32_16x16x32_bf16(k1, qf1, a, 0, 0, 0);
;     sa[kt] = a;
;   }
;   const int lo = has_prev ? (i_q + 1) : ((i_q + 1) > 128 ? (i_q + 1) : 128);
;   const unsigned span = (unsigned)(i_q + 128 - lo);
;   const int dbase = q4 * 4 - lo;
;   float mx = -INFINITY;
; #pragma unroll
;   for (int kt = 0; kt < 9; ++kt) {
; #pragma unroll
;     for (int r = 0; r < 4; ++r) {
;       const int d = (kt0 + kt) * 16 + r + dbase;
;       const float v = ((unsigned)d <= span) ? sa[kt][r] : -INFINITY;
;       sa[kt][r] = v; mx = fmaxf(mx, v);
;     }
;   }
; __device__ __forceinline__ void attn_block_unit(const Params& p, int bu, char* lds, int tid) {
;     ...
;   const int pl = lane & 15;
.LBB0_524:
	s_or_b64 exec, exec, s[6:7]
	s_lshr_b32 s6, s83, 4
	v_readlane_b32 s16, v244, 35
	s_and_b32 s6, s6, 1
	v_readlane_b32 s18, v244, 37
	v_readlane_b32 s19, v244, 38
	s_and_b32 s72, s82, 15
	s_lshl_b32 s76, s6, 9
	s_lshl_b32 s6, s6, 4
	s_mov_b64 s[10:11], s[18:19]
	s_add_u32 s86, s10, s6
	s_addc_u32 s87, s11, 0
	s_cmp_eq_u32 s14, 0
	s_cselect_b64 vcc, -1, 0
	v_cndmask_b32_e64 v3, v183, 8, vcc
	v_lshl_or_b32 v2, v3, 4, v78
	v_cndmask_b32_e32 v4, v113, v114, vcc
	v_mul_u32_u24_e32 v7, 0x90, v2
	v_lshl_or_b32 v2, v4, 4, v78
	v_cndmask_b32_e32 v5, v115, v116, vcc
	v_mul_u32_u24_e32 v8, 0x90, v2
	v_lshl_or_b32 v2, v5, 4, v78
	v_cndmask_b32_e32 v10, v117, v118, vcc
	v_mul_u32_u24_e32 v9, 0x90, v2
	v_lshl_or_b32 v2, v10, 4, v78
	v_cndmask_b32_e32 v12, v119, v120, vcc
	v_mul_u32_u24_e32 v11, 0x90, v2
	v_lshl_or_b32 v2, v12, 4, v78
	v_cndmask_b32_e32 v14, v121, v122, vcc
	v_mul_u32_u24_e32 v13, 0x90, v2
	v_lshl_or_b32 v2, v14, 4, v78
	v_cndmask_b32_e32 v16, v123, v124, vcc
	v_mul_u32_u24_e32 v15, 0x90, v2
	v_lshl_or_b32 v2, v16, 4, v78
	v_cndmask_b32_e32 v18, v125, v126, vcc
	v_cndmask_b32_e32 v20, v81, v127, vcc
	v_mul_u32_u24_e32 v17, 0x90, v2
	v_lshl_or_b32 v2, v18, 4, v78
	v_sub_u32_e32 v21, v20, v81
	v_mul_u32_u24_e32 v19, 0x90, v2
	v_sub_u32_e32 v2, v20, v128
	v_add_u32_e32 v21, 0xffffff80, v21
	v_add_u32_e32 v22, v20, v129
	v_cmp_lt_u32_e64 s[6:7], v2, v21
	v_cmp_lt_u32_e64 s[8:9], v22, v21
	v_add_u32_e32 v22, -2, v2
	v_add_u32_e32 v2, -3, v2
	v_readlane_b32 s17, v244, 36
	v_cmp_lt_u32_e64 s[10:11], v22, v21
	v_cmp_lt_u32_e64 s[12:13], v2, v21
	v_sub_u32_e32 v2, v20, v130
	v_add_u32_e32 v22, v20, v131
	v_readlane_b32 s20, v244, 39
	v_readlane_b32 s21, v244, 40
	v_cmp_lt_u32_e64 s[14:15], v2, v21
	v_cmp_lt_u32_e64 s[16:17], v22, v21
	v_add_u32_e32 v22, -2, v2
	v_add_u32_e32 v2, -3, v2
	v_readlane_b32 s22, v244, 41
	v_readlane_b32 s23, v244, 42
	v_readlane_b32 s24, v244, 43
	v_readlane_b32 s25, v244, 44
	v_cmp_lt_u32_e64 s[18:19], v22, v21
	v_cmp_lt_u32_e64 s[20:21], v2, v21
	v_sub_u32_e32 v2, v20, v132
	v_add_u32_e32 v22, v20, v133
	v_readlane_b32 s26, v244, 45
	v_readlane_b32 s27, v244, 46
	v_readlane_b32 s28, v244, 47
	v_readlane_b32 s29, v244, 48
	v_cmp_lt_u32_e64 s[22:23], v2, v21
	v_cmp_lt_u32_e64 s[24:25], v22, v21
	v_add_u32_e32 v22, -2, v2
	v_add_u32_e32 v2, -3, v2
	v_readlane_b32 s30, v244, 49
	v_readlane_b32 s31, v244, 50
	v_cmp_lt_u32_e64 s[26:27], v22, v21
	v_cmp_lt_u32_e64 s[28:29], v2, v21
	v_sub_u32_e32 v2, v20, v135
	v_add_u32_e32 v22, v20, v136
	v_cmp_lt_u32_e64 s[30:31], v2, v21
	v_cmp_lt_u32_e64 s[34:35], v22, v21
	v_add_u32_e32 v22, -2, v2
	v_add_u32_e32 v2, -3, v2
	v_cmp_lt_u32_e64 s[36:37], v22, v21
	v_cmp_lt_u32_e64 s[38:39], v2, v21
	v_sub_u32_e32 v2, v20, v137
	v_add_u32_e32 v22, v20, v138
	v_cmp_lt_u32_e64 s[40:41], v2, v21
	v_cmp_lt_u32_e64 s[42:43], v22, v21
	v_add_u32_e32 v22, -2, v2
	v_add_u32_e32 v2, -3, v2
	v_cmp_lt_u32_e64 s[44:45], v22, v21
	v_cmp_lt_u32_e64 s[46:47], v2, v21
	v_sub_u32_e32 v2, v20, v139
	v_add_u32_e32 v22, v20, v140
	v_cmp_lt_u32_e64 s[48:49], v2, v21
	v_cmp_lt_u32_e64 s[50:51], v22, v21
	v_add_u32_e32 v22, -2, v2
	v_add_u32_e32 v2, -3, v2
	v_cmp_lt_u32_e64 s[52:53], v22, v21
	v_cmp_lt_u32_e64 s[54:55], v2, v21
	v_sub_u32_e32 v2, v20, v141
	v_add_u32_e32 v22, v20, v142
	v_cmp_lt_u32_e64 s[56:57], v2, v21
	v_cmp_lt_u32_e64 s[58:59], v22, v21
	v_add_u32_e32 v22, -2, v2
	v_add_u32_e32 v2, -3, v2
	v_cmp_lt_u32_e64 s[60:61], v22, v21
	v_cmp_lt_u32_e64 s[62:63], v2, v21
	v_sub_u32_e32 v2, v20, v143
	v_add_u32_e32 v22, v20, v144
	v_cmp_lt_u32_e64 s[66:67], v22, v21
	v_add_u32_e32 v22, -2, v2
	v_cmp_lt_u32_e64 s[64:65], v2, v21
	v_cmp_lt_u32_e64 s[68:69], v22, v21
	v_add_u32_e32 v2, -3, v2
	v_lshl_or_b32 v22, s70, 11, v81
	v_cmp_lt_u32_e64 s[70:71], v2, v21
	v_lshl_or_b32 v2, s72, 7, v22
	v_lshlrev_b32_e32 v56, 5, v3
	v_ashrrev_i32_e32 v3, 31, v2
	s_movk_i32 s74, 0x1800
	v_sub_u32_e32 v23, v20, v145
	v_lshlrev_b32_e32 v57, 5, v4
	v_lshlrev_b32_e32 v58, 5, v5
	v_mad_i64_i32 v[4:5], s[74:75], v2, s74, 0
	v_lshlrev_b64 v[2:3], 10, v[2:3]
	v_cmp_lt_u32_e64 s[72:73], v23, v21
	v_add_u32_e32 v20, v20, v146
	v_add_u32_e32 v22, -2, v23
	v_add_u32_e32 v23, -3, v23
	v_or_b32_e32 v4, s76, v4
	v_or_b32_e32 v2, s76, v2
	v_lshlrev_b32_e32 v59, 5, v10
	v_lshlrev_b32_e32 v60, 5, v12
	v_lshlrev_b32_e32 v61, 5, v14
	v_lshlrev_b32_e32 v62, 5, v16
	v_lshlrev_b32_e32 v63, 5, v18
	v_lshl_add_u64 v[24:25], v[92:93], 0, v[4:5]
	v_lshl_add_u64 v[26:27], v[94:95], 0, v[2:3]
	v_add_u32_e32 v64, v112, v7
	v_add_u32_e32 v65, v112, v8
	v_add_u32_e32 v66, v112, v9
	v_add_u32_e32 v67, v112, v11
	v_add_u32_e32 v68, v112, v13
	v_add_u32_e32 v69, v112, v15
	v_add_u32_e32 v70, v112, v17
	v_add_u32_e32 v71, v112, v19
	v_cmp_lt_u32_e64 s[74:75], v20, v21
	v_cmp_lt_u32_e64 s[76:77], v22, v21
	v_cmp_lt_u32_e64 s[78:79], v23, v21
	s_mov_b64 s[88:89], 0
	global_load_dword v232, v6, s[86:87]
	global_load_dwordx4 v[224:227], v[24:25], off offset:1024
	global_load_dwordx4 v[228:231], v[24:25], off offset:1088
	s_waitcnt vmcnt(0) lgkmcnt(0)
	s_barrier
.LBB0_525:
	s_waitcnt vmcnt(4)
	v_mov_b32_e32 v2, v232
	v_mov_b32_e32 v8, v224
	v_mov_b32_e32 v9, v225
	v_mov_b32_e32 v10, v226
	v_mov_b32_e32 v11, v227
	v_mov_b32_e32 v12, v228
	v_mov_b32_e32 v13, v229
	v_mov_b32_e32 v14, v230
	v_mov_b32_e32 v15, v231
	s_cmpk_eq_i32 s88, 0x180
	s_cbranch_scc1 .Lq_pf_skip
	v_lshl_add_u64 v[4:5], v[24:25], 0, s[88:89]
	global_load_dword v232, v6, s[86:87] offset:4
	global_load_dwordx4 v[224:227], v[4:5], off offset:1152
	global_load_dwordx4 v[228:231], v[4:5], off offset:1216
; #define LAS __attribute__((address_space(3)))
; template <bool LDSRC>
; __device__ __forceinline__ void attn_core(const Params& p, const int lane, const char* kptr, const int kstride, const char* vptr, const int vstride,
;                                           const int kt0, const int has_prev, const int row_q, const int h_q, const int i_q) {
;     ...
; #pragma unroll
;   for (int kt = 0; kt < 9; ++kt) {
;     int T = kt0 + kt; if (!has_prev && T < 8) T = 8;
;     const char* kp = kptr + (T * 16 + pl) * kstride + q4 * 16;
;     bf16x8 k0, k1;
;     if constexpr (LDSRC) { k0 = *(const LAS bf16x8*)(const LAS char*)kp; k1 = *(const LAS bf16x8*)(const LAS char*)(kp + 64); }
;     else { k0 = *(const bf16x8*)kp; k1 = *(const bf16x8*)(kp + 64); }
;     f32x4 a = f32x4{0.f, 0.f, 0.f, 0.f};
;     a = __builtin_amdgcn_mfma_f32_16x16x32_bf16(k0, qf0, a, 0, 0, 0);
;     a = __builtin_amdgcn_mfma_f32_16x16x32_bf16(k1, qf1, a, 0, 0, 0);
;     sa[kt] = a;
;   }
;   const int lo = has_prev ? (i_q + 1) : ((i_q + 1) > 128 ? (i_q + 1) : 128);
;   const unsigned span = (unsigned)(i_q + 128 - lo);
;   const int dbase = q4 * 4 - lo;
;   float mx = -INFINITY;
; #pragma unroll
;   for (int kt = 0; kt < 9; ++kt) {
; #pragma unroll
;     for (int r = 0; r < 4; ++r) {
;       const int d = (kt0 + kt) * 16 + r + dbase;
;       const float v = ((unsigned)d <= span) ? sa[kt][r] : -INFINITY;
;       sa[kt][r] = v; mx = fmaxf(mx, v);
;     }
;   }
;   mx = fmaxf(mx, __shfl_xor(mx, 16)); mx = fmaxf(mx, __shfl_xor(mx, 32));
.Lq_pf_skip:
	ds_read_b128 v[16:19], v64
	ds_read_b128 v[20:23], v64 offset:64
	s_mov_b32 s84, 0xff800000
	v_xor_b32_e32 v7, 16, v159
	v_add_u32_e32 v76, v148, v57
	v_add_u32_e32 v97, v147, v58
	v_add_u32_e32 v99, v147, v59
	s_waitcnt lgkmcnt(1)
	v_mfma_f32_16x16x32_bf16 v[16:19], v[16:19], v[8:11], 0
	s_waitcnt lgkmcnt(0)
	v_mfma_f32_16x16x32_bf16 v[16:19], v[20:23], v[12:15], v[16:19]
	ds_read_b128 v[20:23], v65
	ds_read_b128 v[28:31], v65 offset:64
	s_waitcnt lgkmcnt(1)
	v_mfma_f32_16x16x32_bf16 v[20:23], v[20:23], v[8:11], 0
	s_nop 3
	v_cndmask_b32_e64 v3, v16, v158, s[6:7]
	v_cndmask_b32_e64 v4, v17, v158, s[8:9]
	v_max3_f32 v5, v3, s84, v4
	s_waitcnt lgkmcnt(0)
	v_mfma_f32_16x16x32_bf16 v[20:23], v[28:31], v[12:15], v[20:23]
	ds_read_b128 v[28:31], v66
	ds_read_b128 v[32:35], v66 offset:64
	v_and_b32_e32 v16, 64, v159
	v_add_u32_e32 v16, 64, v16
	s_waitcnt lgkmcnt(1)
	v_mfma_f32_16x16x32_bf16 v[28:31], v[28:31], v[8:11], 0
	s_nop 1
	v_cndmask_b32_e64 v22, v22, v158, s[18:19]
	v_cndmask_b32_e64 v23, v23, v158, s[20:21]
	v_cmp_lt_i32_e32 vcc, v7, v16
	s_waitcnt lgkmcnt(0)
	v_mfma_f32_16x16x32_bf16 v[28:31], v[32:35], v[12:15], v[28:31]
	ds_read_b128 v[32:35], v67
	ds_read_b128 v[36:39], v67 offset:64
	v_cndmask_b32_e32 v7, v159, v7, vcc
	v_lshlrev_b32_e32 v7, 2, v7
	s_waitcnt lgkmcnt(1)
	v_mfma_f32_16x16x32_bf16 v[32:35], v[32:35], v[8:11], 0
	s_nop 1
	v_cndmask_b32_e64 v30, v30, v158, s[26:27]
	v_cndmask_b32_e64 v31, v31, v158, s[28:29]
	s_waitcnt lgkmcnt(0)
	v_mfma_f32_16x16x32_bf16 v[32:35], v[36:39], v[12:15], v[32:35]
	ds_read_b128 v[36:39], v68
	ds_read_b128 v[40:43], v68 offset:64
	s_waitcnt lgkmcnt(1)
	v_mfma_f32_16x16x32_bf16 v[36:39], v[36:39], v[8:11], 0
	s_nop 3
	v_cndmask_b32_e64 v32, v32, v158, s[30:31]
	v_cndmask_b32_e64 v33, v33, v158, s[34:35]
	v_cndmask_b32_e64 v34, v34, v158, s[36:37]
	s_waitcnt lgkmcnt(0)
	v_mfma_f32_16x16x32_bf16 v[36:39], v[40:43], v[12:15], v[36:39]
	ds_read_b128 v[40:43], v69
	ds_read_b128 v[44:47], v69 offset:64
	v_cndmask_b32_e64 v35, v35, v158, s[38:39]
	s_waitcnt lgkmcnt(1)
	v_mfma_f32_16x16x32_bf16 v[40:43], v[40:43], v[8:11], 0
	s_nop 2
	v_cndmask_b32_e64 v38, v38, v158, s[44:45]
	v_cndmask_b32_e64 v39, v39, v158, s[46:47]
	s_waitcnt lgkmcnt(0)
	v_mfma_f32_16x16x32_bf16 v[40:43], v[44:47], v[12:15], v[40:43]
	ds_read_b128 v[44:47], v70
	ds_read_b128 v[48:51], v70 offset:64
	s_waitcnt lgkmcnt(1)
	v_mfma_f32_16x16x32_bf16 v[44:47], v[44:47], v[8:11], 0
	s_nop 3
	v_cndmask_b32_e64 v40, v40, v158, s[48:49]
	v_cndmask_b32_e64 v41, v41, v158, s[50:51]
	v_cndmask_b32_e64 v42, v42, v158, s[52:53]
	s_waitcnt lgkmcnt(0)
	v_mfma_f32_16x16x32_bf16 v[44:47], v[48:51], v[12:15], v[44:47]
	ds_read_b128 v[48:51], v71
	ds_read_b128 v[52:55], v71 offset:64
	v_cndmask_b32_e64 v43, v43, v158, s[54:55]
	s_waitcnt lgkmcnt(1)
	v_mfma_f32_16x16x32_bf16 v[48:51], v[48:51], v[8:11], 0
	s_nop 2
	v_cndmask_b32_e64 v46, v46, v158, s[60:61]
	v_cndmask_b32_e64 v47, v47, v158, s[62:63]
	s_waitcnt lgkmcnt(0)
	v_mfma_f32_16x16x32_bf16 v[48:51], v[52:55], v[12:15], v[48:51]
	ds_read_b128 v[52:55], v156
	ds_read_b128 v[72:75], v156 offset:64
	s_waitcnt lgkmcnt(1)
	v_mfma_f32_16x16x32_bf16 v[8:11], v[52:55], v[8:11], 0
	v_cndmask_b32_e64 v52, v28, v158, s[22:23]
	v_cndmask_b32_e64 v53, v29, v158, s[24:25]
	v_cndmask_b32_e64 v54, v36, v158, s[40:41]
	s_waitcnt lgkmcnt(0)
	v_mfma_f32_16x16x32_bf16 v[8:11], v[72:75], v[12:15], v[8:11]
	v_cndmask_b32_e64 v12, v18, v158, s[10:11]
	v_cndmask_b32_e64 v13, v19, v158, s[12:13]
	v_max3_f32 v5, v5, v12, v13
	v_cndmask_b32_e64 v14, v20, v158, s[14:15]
	v_cndmask_b32_e64 v15, v21, v158, s[16:17]
	v_max3_f32 v5, v5, v14, v15
	v_max3_f32 v5, v5, v22, v23
	v_max3_f32 v5, v5, v52, v53
	v_max3_f32 v5, v5, v30, v31
	v_max3_f32 v5, v5, v32, v33
	v_max3_f32 v5, v5, v34, v35
	v_cndmask_b32_e64 v55, v37, v158, s[42:43]
	v_max3_f32 v5, v5, v54, v55
	v_max3_f32 v5, v5, v38, v39
	v_max3_f32 v5, v5, v40, v41
	v_max3_f32 v5, v5, v42, v43
	v_cndmask_b32_e64 v73, v44, v158, s[56:57]
	v_cndmask_b32_e64 v74, v45, v158, s[58:59]
	v_max3_f32 v5, v5, v73, v74
	v_max3_f32 v5, v5, v46, v47
	v_cndmask_b32_e64 v48, v48, v158, s[64:65]
	v_cndmask_b32_e64 v49, v49, v158, s[66:67]
	v_max3_f32 v5, v5, v48, v49
	v_cndmask_b32_e64 v50, v50, v158, s[68:69]
	v_cndmask_b32_e64 v51, v51, v158, s[70:71]
	v_max3_f32 v5, v5, v50, v51
	v_cndmask_b32_e64 v8, v8, v158, s[72:73]
	v_cndmask_b32_e64 v9, v9, v158, s[74:75]
	v_max3_f32 v5, v5, v8, v9
	v_cndmask_b32_e64 v10, v10, v158, s[76:77]
	v_cndmask_b32_e64 v11, v11, v158, s[78:79]
	v_max3_f32 v5, v5, v10, v11
	ds_bpermute_b32 v17, v7, v5
	s_waitcnt lgkmcnt(0)
	v_max_f32_e32 v17, v17, v17
	v_max_f32_e32 v5, v5, v17
	v_xor_b32_e32 v17, 32, v159
	v_cmp_lt_i32_e32 vcc, v17, v16
	s_nop 1
	v_cndmask_b32_e32 v16, v159, v17, vcc
	v_lshlrev_b32_e32 v72, 2, v16
	ds_bpermute_b32 v16, v72, v5
	s_waitcnt lgkmcnt(0)
; __device__ __forceinline__ unsigned pk2(float lo, float hi) { f32x2 v = {lo, hi}; bf16v2_t b = __builtin_convertvector(v, bf16v2_t); return __builtin_bit_cast(unsigned, b); }
; #define LAS __attribute__((address_space(3)))
; template <bool LDSRC>
; __device__ __forceinline__ void attn_core(const Params& p, const int lane, const char* kptr, const int kstride, const char* vptr, const int vstride,
;                                           const int kt0, const int has_prev, const int row_q, const int h_q, const int i_q) {
;     ...
;   const float mfin = fmaxf(mx * 0.125f, sink);
;   const float cl = 0.125f * 1.4426950408889634f, ml = mfin * 1.4426950408889634f;
;   float sum = 0.f;
; #pragma unroll
;   for (int kt = 0; kt < 9; ++kt) {
; #pragma unroll
;     for (int r = 0; r < 4; ++r) { const float e = __builtin_amdgcn_exp2f(fmaf(sa[kt][r], cl, -ml)); sa[kt][r] = e; sum += e; }
;   }
;   sum += __shfl_xor(sum, 16); sum += __shfl_xor(sum, 32);
;   const float inv = 1.f / (sum + __builtin_amdgcn_exp2f((sink - mfin) * 1.4426950408889634f));
;   f32x4 oa[4];
; #pragma unroll
;   for (int dt = 0; dt < 4; ++dt) oa[dt] = f32x4{0.f, 0.f, 0.f, 0.f};
; #pragma unroll
;   for (int pp = 0; pp < 5; ++pp) {
;     const int kA = 2 * pp, kB = (2 * pp + 1 < 9) ? 2 * pp + 1 : 2 * pp;
;     u32x4 pw;
;     pw.x = pk2(sa[kA][0] * inv, sa[kA][1] * inv); pw.y = pk2(sa[kA][2] * inv, sa[kA][3] * inv);
;     if (2 * pp + 1 < 9) { pw.z = pk2(sa[kB][0] * inv, sa[kB][1] * inv); pw.w = pk2(sa[kB][2] * inv, sa[kB][3] * inv); }
;     else { pw.z = 0u; pw.w = 0u; }
;     const bf16x8 pf = __builtin_bit_cast(bf16x8, pw);
;     if constexpr (LDSRC) {
;       int TA = kt0 + 2 * pp, TB = kt0 + ((2 * pp + 1 < 9) ? 2 * pp + 1 : 2 * pp);
;       if (!has_prev) { if (TA < 8) TA = 8; if (TB < 8) TB = 8; }
; #pragma unroll
;       for (int dt = 0; dt < 4; ++dt) {
;         const char* vp = vptr + (dt * 16 + pl) * vstride + q4 * 8;
;         const u32x2 va = *(const LAS u32x2*)(const LAS char*)(vp + TA * 32), vb = *(const LAS u32x2*)(const LAS char*)(vp + TB * 32);
;         oa[dt] = __builtin_amdgcn_mfma_f32_16x16x32_bf16(__builtin_bit_cast(bf16x8, u32x4{va.x, va.y, vb.x, vb.y}), pf, oa[dt], 0, 0, 0);
	v_max_f32_e32 v16, v16, v16
	v_max_f32_e32 v5, v5, v16
	v_mul_f32_e32 v5, 0x3e000000, v5
	v_max_f32_e32 v16, v2, v2
	v_max_f32_e32 v5, v5, v16
	v_mul_f32_e32 v75, 0xbfb8aa3b, v5
	v_fmamk_f32 v3, v3, 0x3e38aa3b, v75
	v_exp_f32_e32 v16, v3
	v_fmamk_f32 v3, v4, 0x3e38aa3b, v75
	v_exp_f32_e32 v17, v3
	v_fmamk_f32 v3, v12, 0x3e38aa3b, v75
	v_exp_f32_e32 v18, v3
	v_fmamk_f32 v3, v13, 0x3e38aa3b, v75
	v_exp_f32_e32 v19, v3
	v_fmamk_f32 v3, v14, 0x3e38aa3b, v75
	v_exp_f32_e32 v20, v3
	v_fmamk_f32 v3, v15, 0x3e38aa3b, v75
	v_exp_f32_e32 v21, v3
	v_fmamk_f32 v3, v22, 0x3e38aa3b, v75
	v_exp_f32_e32 v28, v3
	v_fmamk_f32 v3, v23, 0x3e38aa3b, v75
	v_exp_f32_e32 v29, v3
	v_fmamk_f32 v3, v52, 0x3e38aa3b, v75
	v_exp_f32_e32 v22, v3
	v_fmamk_f32 v3, v53, 0x3e38aa3b, v75
	v_exp_f32_e32 v23, v3
	v_fmamk_f32 v3, v30, 0x3e38aa3b, v75
	v_exp_f32_e32 v30, v3
	v_fmamk_f32 v3, v31, 0x3e38aa3b, v75
	v_exp_f32_e32 v31, v3
	v_fmamk_f32 v3, v32, 0x3e38aa3b, v75
	v_exp_f32_e32 v32, v3
	v_fmamk_f32 v3, v33, 0x3e38aa3b, v75
	v_exp_f32_e32 v33, v3
	v_fmamk_f32 v3, v34, 0x3e38aa3b, v75
	v_exp_f32_e32 v36, v3
	v_fmamk_f32 v3, v35, 0x3e38aa3b, v75
	v_exp_f32_e32 v37, v3
	v_fmamk_f32 v3, v54, 0x3e38aa3b, v75
	v_exp_f32_e32 v34, v3
	v_fmamk_f32 v3, v55, 0x3e38aa3b, v75
	v_exp_f32_e32 v35, v3
	v_fmamk_f32 v3, v38, 0x3e38aa3b, v75
	v_exp_f32_e32 v38, v3
	v_fmamk_f32 v3, v39, 0x3e38aa3b, v75
	v_exp_f32_e32 v39, v3
	v_fmamk_f32 v3, v40, 0x3e38aa3b, v75
	v_exp_f32_e32 v40, v3
	v_fmamk_f32 v3, v41, 0x3e38aa3b, v75
	v_exp_f32_e32 v41, v3
	v_fmamk_f32 v3, v42, 0x3e38aa3b, v75
	v_exp_f32_e32 v44, v3
	v_fmamk_f32 v3, v43, 0x3e38aa3b, v75
	v_exp_f32_e32 v45, v3
	v_fmamk_f32 v3, v73, 0x3e38aa3b, v75
	v_exp_f32_e32 v42, v3
	v_fmamk_f32 v3, v74, 0x3e38aa3b, v75
	v_exp_f32_e32 v43, v3
	v_fmamk_f32 v3, v46, 0x3e38aa3b, v75
	v_exp_f32_e32 v46, v3
	v_fmamk_f32 v3, v47, 0x3e38aa3b, v75
	v_exp_f32_e32 v47, v3
	v_fmamk_f32 v3, v48, 0x3e38aa3b, v75
	v_exp_f32_e32 v48, v3
	v_fmamk_f32 v3, v49, 0x3e38aa3b, v75
	v_exp_f32_e32 v49, v3
	v_fmamk_f32 v3, v50, 0x3e38aa3b, v75
	v_exp_f32_e32 v52, v3
	v_fmamk_f32 v3, v51, 0x3e38aa3b, v75
	v_exp_f32_e32 v53, v3
	v_fmamk_f32 v3, v8, 0x3e38aa3b, v75
	v_exp_f32_e32 v50, v3
	v_fmamk_f32 v3, v9, 0x3e38aa3b, v75
	v_sub_f32_e32 v2, v2, v5
	v_exp_f32_e32 v51, v3
	v_fmamk_f32 v3, v10, 0x3e38aa3b, v75
	v_fmac_f32_e32 v75, 0x3e38aa3b, v11
	v_mul_f32_e32 v2, 0x3fb8aa3b, v2
	v_add_u32_e32 v12, v147, v56
	v_add_u32_e32 v14, v147, v57
	v_add_u32_e32 v74, v148, v56
	v_exp_f32_e32 v54, v3
	v_exp_f32_e32 v55, v75
	v_exp_f32_e32 v73, v2
	ds_read_b64 v[2:3], v12 offset:36864
	ds_read_b64 v[4:5], v14 offset:36864
	ds_read_b64 v[8:9], v12 offset:45312
	ds_read_b64 v[10:11], v14 offset:45312
	ds_read_b64 v[12:13], v12 offset:53760
	ds_read_b64 v[14:15], v14 offset:53760
	ds_read_b64 v[74:75], v74 offset:36864
	ds_read_b64 v[76:77], v76 offset:36864
	ds_read_b64 v[106:107], v97 offset:36864
	ds_read_b64 v[108:109], v99 offset:36864
	ds_read_b64 v[160:161], v97 offset:45312
	ds_read_b64 v[162:163], v99 offset:45312
	ds_read_b64 v[164:165], v97 offset:53760
	ds_read_b64 v[166:167], v99 offset:53760
	v_add_u32_e32 v97, v148, v58
	ds_read_b64 v[168:169], v97 offset:36864
	v_add_u32_e32 v97, v148, v59
	ds_read_b64 v[170:171], v97 offset:36864
	v_add_u32_e32 v97, v147, v60
	v_add_u32_e32 v99, v147, v61
	ds_read_b64 v[172:173], v97 offset:36864
	ds_read_b64 v[174:175], v99 offset:36864
	ds_read_b64 v[176:177], v97 offset:45312
	ds_read_b64 v[178:179], v99 offset:45312
	ds_read_b64 v[188:189], v97 offset:53760
	ds_read_b64 v[190:191], v99 offset:53760
	v_add_u32_e32 v97, v148, v60
	ds_read_b64 v[192:193], v97 offset:36864
	v_add_u32_e32 v97, v148, v61
	ds_read_b64 v[194:195], v97 offset:36864
	v_add_u32_e32 v97, v147, v62
	v_add_u32_e32 v99, v147, v63
	ds_read_b64 v[196:197], v97 offset:36864
	ds_read_b64 v[198:199], v99 offset:36864
	ds_read_b64 v[200:201], v97 offset:45312
	ds_read_b64 v[202:203], v99 offset:45312
	ds_read_b64 v[204:205], v97 offset:53760
	ds_read_b64 v[206:207], v99 offset:53760
	v_add_u32_e32 v97, v148, v62
	ds_read_b64 v[208:209], v97 offset:36864
	v_add_u32_e32 v97, v148, v63
	ds_read_b64 v[210:211], v97 offset:36864
	v_add_f32_e32 v97, 0, v16
	v_add_f32_e32 v97, v17, v97
	v_add_f32_e32 v97, v18, v97
	v_add_f32_e32 v97, v19, v97
	v_add_f32_e32 v97, v20, v97
	v_add_f32_e32 v97, v21, v97
	v_add_f32_e32 v97, v28, v97
	v_add_f32_e32 v97, v29, v97
	v_add_f32_e32 v97, v22, v97
	v_add_f32_e32 v97, v23, v97
	v_add_f32_e32 v97, v30, v97
	v_add_f32_e32 v97, v31, v97
	v_add_f32_e32 v97, v32, v97
	v_add_f32_e32 v97, v33, v97
	v_add_f32_e32 v97, v36, v97
	v_add_f32_e32 v97, v37, v97
	v_add_f32_e32 v97, v34, v97
	v_add_f32_e32 v97, v35, v97
	v_add_f32_e32 v97, v38, v97
	v_add_f32_e32 v97, v39, v97
	v_add_f32_e32 v97, v40, v97
	v_add_f32_e32 v97, v41, v97
	v_add_f32_e32 v97, v44, v97
	v_add_f32_e32 v97, v45, v97
	v_add_f32_e32 v97, v42, v97
	v_add_f32_e32 v97, v43, v97
	v_add_f32_e32 v97, v46, v97
	v_add_f32_e32 v97, v47, v97
	v_add_f32_e32 v97, v48, v97
	v_add_f32_e32 v97, v49, v97
	v_add_f32_e32 v97, v52, v97
	v_add_f32_e32 v97, v53, v97
	v_add_f32_e32 v97, v50, v97
	v_add_f32_e32 v97, v51, v97
	v_add_f32_e32 v97, v54, v97
	v_add_f32_e32 v97, v55, v97
	ds_bpermute_b32 v7, v7, v97
	s_waitcnt lgkmcnt(0)
; #define LAS __attribute__((address_space(3)))
; template <bool LDSRC>
; __device__ __forceinline__ void attn_core(const Params& p, const int lane, const char* kptr, const int kstride, const char* vptr, const int vstride,
;                                           const int kt0, const int has_prev, const int row_q, const int h_q, const int i_q) {
;     ...
;   sum += __shfl_xor(sum, 16); sum += __shfl_xor(sum, 32);
;   const float inv = 1.f / (sum + __builtin_amdgcn_exp2f((sink - mfin) * 1.4426950408889634f));
;   f32x4 oa[4];
; #pragma unroll
;   for (int dt = 0; dt < 4; ++dt) oa[dt] = f32x4{0.f, 0.f, 0.f, 0.f};
; #pragma unroll
;   for (int pp = 0; pp < 5; ++pp) {
;     const int kA = 2 * pp, kB = (2 * pp + 1 < 9) ? 2 * pp + 1 : 2 * pp;
;     u32x4 pw;
;     pw.x = pk2(sa[kA][0] * inv, sa[kA][1] * inv); pw.y = pk2(sa[kA][2] * inv, sa[kA][3] * inv);
;     if (2 * pp + 1 < 9) { pw.z = pk2(sa[kB][0] * inv, sa[kB][1] * inv); pw.w = pk2(sa[kB][2] * inv, sa[kB][3] * inv); }
;     else { pw.z = 0u; pw.w = 0u; }
;     const bf16x8 pf = __builtin_bit_cast(bf16x8, pw);
;     if constexpr (LDSRC) {
;       int TA = kt0 + 2 * pp, TB = kt0 + ((2 * pp + 1 < 9) ? 2 * pp + 1 : 2 * pp);
;       if (!has_prev) { if (TA < 8) TA = 8; if (TB < 8) TB = 8; }
; #pragma unroll
;       for (int dt = 0; dt < 4; ++dt) {
;         const char* vp = vptr + (dt * 16 + pl) * vstride + q4 * 8;
;         const u32x2 va = *(const LAS u32x2*)(const LAS char*)(vp + TA * 32), vb = *(const LAS u32x2*)(const LAS char*)(vp + TB * 32);
;         oa[dt] = __builtin_amdgcn_mfma_f32_16x16x32_bf16(__builtin_bit_cast(bf16x8, u32x4{va.x, va.y, vb.x, vb.y}), pf, oa[dt], 0, 0, 0);
;       }
;     } else {
; #pragma unroll
;       for (int dt = 0; dt < 4; ++dt) oa[dt] = __builtin_amdgcn_mfma_f32_16x16x32_bf16(__builtin_bit_cast(bf16x8, vfr[pp][dt]), pf, oa[dt], 0, 0, 0);
;     }
;   }
;   bf16_t* O = (bf16_t*)(ws + OFF_O);
; #pragma unroll
;   for (int dt = 0; dt < 4; ++dt) *(u32x2*)(O + (size_t)row_q * 512 + h_q * 64 + dt * 16 + q4 * 4) = pk4(oa[dt]);
; __device__ __forceinline__ void attn_block_unit(const Params& p, int bu, char* lds, int tid) {
;     ...
;   for (int g = 0; g < 4; ++g) {
;     asm volatile("" ::: "memory");
;     attn_core<true>(p, lane, K_l, ATT_KSTR, Vt_l, ATT_VSTR, wid, blk > 0, b * 2048 + blk * 128 + wid * 16 + pl, kv * 4 + g, wid * 16 + pl);
;   }
	v_add_f32_e32 v7, v97, v7
	ds_bpermute_b32 v72, v72, v7
	s_waitcnt lgkmcnt(0)
	v_add_f32_e32 v7, v7, v72
	v_add_f32_e32 v7, v73, v7
	v_div_scale_f32 v72, vcc, v7, v7, 1.0
	v_rcp_f32_e32 v73, v72
	s_nop 0
	v_fma_f32 v97, -v72, v73, 1.0
	v_fmac_f32_e32 v73, v97, v73
	v_div_scale_f32 v97, vcc, 1.0, v7, 1.0
	v_mul_f32_e32 v99, v97, v73
	v_fma_f32 v101, -v72, v99, v97
	v_fmac_f32_e32 v99, v101, v73
	v_fma_f32 v72, -v72, v99, v97
	v_div_fmas_f32 v72, v72, v73, v99
	v_div_fixup_f32 v72, v72, v7, 1.0
	v_pk_mul_f32 v[16:17], v[16:17], v[72:73] op_sel_hi:[1,0]
	v_pk_mul_f32 v[18:19], v[18:19], v[72:73] op_sel_hi:[1,0]
	v_cvt_pk_bf16_f32 v16, v16, v17
	v_cvt_pk_bf16_f32 v17, v18, v19
	v_pk_mul_f32 v[18:19], v[20:21], v[72:73] op_sel_hi:[1,0]
	v_pk_mul_f32 v[20:21], v[28:29], v[72:73] op_sel_hi:[1,0]
	v_cvt_pk_bf16_f32 v18, v18, v19
	v_cvt_pk_bf16_f32 v19, v20, v21
	v_pk_mul_f32 v[20:21], v[22:23], v[72:73] op_sel_hi:[1,0]
	v_pk_mul_f32 v[22:23], v[30:31], v[72:73] op_sel_hi:[1,0]
	v_mfma_f32_16x16x32_bf16 v[2:5], v[2:5], v[16:19], 0
	v_cvt_pk_bf16_f32 v20, v20, v21
	v_cvt_pk_bf16_f32 v21, v22, v23
	v_pk_mul_f32 v[22:23], v[32:33], v[72:73] op_sel_hi:[1,0]
	v_mfma_f32_16x16x32_bf16 v[8:11], v[8:11], v[16:19], 0
	v_mul_f32_e64 v28, v36, v72
	v_mul_f32_e64 v29, v37, v72
	v_cvt_pk_bf16_f32 v22, v22, v23
	v_cvt_pk_bf16_f32 v23, v28, v29
	v_mfma_f32_16x16x32_bf16 v[12:15], v[12:15], v[16:19], 0
	v_mul_f32_e64 v28, v44, v72
	v_mul_f32_e64 v29, v45, v72
	v_mov_b32_e32 v7, v6
	v_mfma_f32_16x16x32_bf16 v[16:19], v[74:77], v[16:19], 0
	v_mfma_f32_16x16x32_bf16 v[16:19], v[168:171], v[20:23], v[16:19]
	v_mfma_f32_16x16x32_bf16 v[2:5], v[106:109], v[20:23], v[2:5]
	v_mfma_f32_16x16x32_bf16 v[8:11], v[160:163], v[20:23], v[8:11]
	v_mfma_f32_16x16x32_bf16 v[12:15], v[164:167], v[20:23], v[12:15]
	v_mul_f32_e64 v20, v34, v72
	v_mul_f32_e64 v21, v35, v72
	v_pk_mul_f32 v[22:23], v[38:39], v[72:73] op_sel_hi:[1,0]
	v_cvt_pk_bf16_f32 v20, v20, v21
	v_cvt_pk_bf16_f32 v21, v22, v23
	v_pk_mul_f32 v[22:23], v[40:41], v[72:73] op_sel_hi:[1,0]
	s_nop 0
	v_cvt_pk_bf16_f32 v22, v22, v23
	v_cvt_pk_bf16_f32 v23, v28, v29
	s_nop 1
	v_mfma_f32_16x16x32_bf16 v[28:31], v[192:195], v[20:23], v[16:19]
	s_nop 2
	v_mul_f32_e64 v16, v42, v72
	v_mul_f32_e64 v17, v43, v72
	v_mfma_f32_16x16x32_bf16 v[2:5], v[172:175], v[20:23], v[2:5]
	v_cvt_pk_bf16_f32 v32, v16, v17
	v_pk_mul_f32 v[16:17], v[46:47], v[72:73] op_sel_hi:[1,0]
	s_nop 0
	v_cvt_pk_bf16_f32 v33, v16, v17
	v_pk_mul_f32 v[16:17], v[48:49], v[72:73] op_sel_hi:[1,0]
	v_mfma_f32_16x16x32_bf16 v[8:11], v[176:179], v[20:23], v[8:11]
	v_cvt_pk_bf16_f32 v34, v16, v17
	v_pk_mul_f32 v[16:17], v[52:53], v[72:73] op_sel_hi:[1,0]
	s_nop 0
	v_cvt_pk_bf16_f32 v35, v16, v17
	v_mfma_f32_16x16x32_bf16 v[12:15], v[188:191], v[20:23], v[12:15]
	s_nop 0
	v_mfma_f32_16x16x32_bf16 v[20:23], v[196:199], v[32:35], v[2:5]
	s_nop 2
	v_mul_f32_e64 v2, v50, v72
	v_mul_f32_e64 v3, v51, v72
	v_mfma_f32_16x16x32_bf16 v[16:19], v[200:203], v[32:35], v[8:11]
	v_cvt_pk_bf16_f32 v4, v2, v3
	v_pk_mul_f32 v[2:3], v[54:55], v[72:73] op_sel_hi:[1,0]
	s_nop 0
	v_cvt_pk_bf16_f32 v5, v2, v3
	v_add_u32_e32 v2, v147, v149
	v_mfma_f32_16x16x32_bf16 v[8:11], v[208:211], v[32:35], v[28:31]
	s_nop 2
	ds_read_b64 v[28:29], v2 offset:36864
	v_mfma_f32_16x16x32_bf16 v[12:15], v[204:207], v[32:35], v[12:15]
	s_waitcnt lgkmcnt(0)
	v_mov_b32_e32 v30, v28
	v_mov_b32_e32 v31, v29
	s_nop 1
	v_mfma_f32_16x16x32_bf16 v[20:23], v[28:31], v[4:7], v[20:23]
	ds_read_b64 v[28:29], v2 offset:45312
	s_waitcnt lgkmcnt(0)
	v_mov_b32_e32 v30, v28
	v_mov_b32_e32 v31, v29
	s_nop 1
	v_mfma_f32_16x16x32_bf16 v[16:19], v[28:31], v[4:7], v[16:19]
	ds_read_b64 v[28:29], v2 offset:53760
	v_add_u32_e32 v2, v148, v149
	s_waitcnt lgkmcnt(0)
	v_mov_b32_e32 v30, v28
	v_mov_b32_e32 v31, v29
	s_nop 1
	v_mfma_f32_16x16x32_bf16 v[12:15], v[28:31], v[4:7], v[12:15]
	ds_read_b64 v[28:29], v2 offset:36864
	s_waitcnt lgkmcnt(0)
	v_mov_b32_e32 v30, v28
	v_mov_b32_e32 v31, v29
	s_nop 1
	v_mfma_f32_16x16x32_bf16 v[2:5], v[28:31], v[4:7], v[8:11]
	s_nop 2
	v_lshl_add_u64 v[8:9], v[26:27], 0, s[88:89]
	s_add_u32 s88, s88, 0x80
	s_addc_u32 s89, s89, 0
	v_cvt_pk_bf16_f32 v10, v20, v21
	v_cvt_pk_bf16_f32 v11, v22, v23
	s_add_u32 s86, s86, 4
	global_store_dwordx2 v[8:9], v[10:11], off offset:-64
	v_cvt_pk_bf16_f32 v10, v16, v17
	v_cvt_pk_bf16_f32 v11, v18, v19
	s_addc_u32 s87, s87, 0
	global_store_dwordx2 v[8:9], v[10:11], off offset:-32
	v_cvt_pk_bf16_f32 v10, v12, v13
	v_cvt_pk_bf16_f32 v11, v14, v15
	v_cvt_pk_bf16_f32 v2, v2, v3
	v_cvt_pk_bf16_f32 v3, v4, v5
	s_cmpk_lg_i32 s88, 0x200
	global_store_dwordx2 v[8:9], v[10:11], off
	global_store_dwordx2 v[8:9], v[2:3], off offset:32
	s_cbranch_scc1 .LBB0_525
	s_add_i32 s83, s83, s33
	s_add_i32 s82, s82, s33
	s_cmpk_gt_i32 s83, 0xff
	s_barrier
	s_cbranch_scc0 .LBB0_502
	s_branch .LBB0_529
